# removed 10 compiler s_nop pads after inline-asm v_min in the Gates epilogue (no hazard: plain VALU producer)
# speedup vs baseline: 1.0015x; 1.0015x over previous
; #define LAS __attribute__((address_space(3)))
; template <int NP> __device__ __forceinline__ void row_scales(float (&rs)[2][4], const float* base, long row0, int fq, float inv_n) {
;     float t[2][4];
; #pragma unroll
;     for (int ai = 0; ai < 2; ++ai)
; #pragma unroll
;         for (int m = 0; m < 4; ++m) { const long row = row0 + ai * 128 + m * 16;
;             if (NP == 16) { const f32x4 v = *(const f32x4*)(base + row * 16 + 4 * fq); t[ai][m] = (v.x + v.y) + (v.z + v.w); }
;             else if (NP == 8) { const f32x2 v = *(const f32x2*)(base + row * 8 + 2 * fq); t[ai][m] = v.x + v.y; }
;             else t[ai][m] = base[row * 4 + fq]; }
; #pragma unroll
;     for (int ai = 0; ai < 2; ++ai)
; #pragma unroll
;         for (int m = 0; m < 4; ++m) rs[ai][m] = rsqrtf(red_fq(t[ai][m]) * inv_n + EPS);
;     __device__ __forceinline__ void operator()(AccT& acc, const Unit& u, int wr, int wc, int fr, int fq, LAS unsigned char*) const {
;         const long row0 = (long)u.pm * 256 + wr * 64 + fr;
;         const size_t tb = ((size_t)(u.pm * 12 + u.pn) * 8 + (wr * 4 + wc)) * 16; const int lane = fq * 16 + fr;
;         float rsa[2][4]; row_scales<16>(rsa, ssqx, row0, fq, 1.f / 1024.f);
; #pragma unroll
;         for (int ai = 0; ai < 2; ++ai)
; #pragma unroll
;             for (int m = 0; m < 4; ++m) {
;                 const float rs = rsa[ai][m] * -LOG2E;
.LBB0_335:
	s_ashr_i32 s1, s0, 31
	s_mul_i32 s8, s0, 12
	s_lshl_b64 s[0:1], s[0:1], 14
	v_lshl_add_u64 v[144:145], v[134:135], 0, s[0:1]
	global_load_dwordx4 v[140:143], v[144:145], off
	s_add_i32 s8, s8, s79
	s_ashr_i32 s9, s8, 31
	s_lshl_b64 s[12:13], s[8:9], 17
	s_movk_i32 s8, 0x2000
	v_add_co_u32_e32 v162, vcc, s8, v144
	s_mov_b32 s0, 0x358637bd
	s_nop 0
	v_addc_co_u32_e32 v163, vcc, 0, v145, vcc
	global_load_dwordx4 v[156:159], v[162:163], off offset:2048
	global_load_dwordx4 v[164:167], v[144:145], off offset:1024
	global_load_dwordx4 v[168:171], v[144:145], off offset:2048
	global_load_dwordx4 v[172:175], v[144:145], off offset:3072
	global_load_dwordx4 v[176:179], v[162:163], off
	global_load_dwordx4 v[180:183], v[162:163], off offset:1024
	global_load_dwordx4 v[184:187], v[162:163], off offset:3072
	s_mov_b32 s18, 0x3a800000
	s_movk_i32 s75, 0xc0
	s_mov_b32 s26, 0x18000
	s_waitcnt vmcnt(0)
	v_mov_b32_e32 v146, v141
	v_mov_b32_e32 v147, v142
	v_mov_b32_e32 v141, v143
	v_pk_add_f32 v[140:141], v[146:147], v[140:141]
	s_nop 0
	v_pk_add_f32 v[150:151], v[140:141], v[140:141] op_sel:[0,1] op_sel_hi:[1,0]
	v_mov_b64_e32 v[140:141], v[164:165]
	v_mov_b64_e32 v[142:143], v[166:167]
	v_mov_b32_e32 v146, v141
	v_mov_b32_e32 v147, v142
	v_mov_b32_e32 v141, v143
	v_pk_add_f32 v[140:141], v[146:147], v[140:141]
	s_nop 0
	v_pk_add_f32 v[160:161], v[140:141], v[140:141] op_sel:[0,1] op_sel_hi:[1,0]
	v_mov_b64_e32 v[140:141], v[168:169]
	v_mov_b64_e32 v[142:143], v[170:171]
	v_mov_b32_e32 v146, v141
	v_mov_b32_e32 v147, v142
	v_mov_b32_e32 v141, v143
	v_pk_add_f32 v[140:141], v[146:147], v[140:141]
	s_nop 0
	v_pk_add_f32 v[152:153], v[140:141], v[140:141] op_sel:[0,1] op_sel_hi:[1,0]
	v_mov_b64_e32 v[140:141], v[172:173]
	v_mov_b64_e32 v[142:143], v[174:175]
	v_mov_b32_e32 v146, v141
	v_mov_b32_e32 v147, v142
	v_mov_b32_e32 v141, v143
	v_pk_add_f32 v[140:141], v[146:147], v[140:141]
	s_nop 0
	v_pk_add_f32 v[148:149], v[140:141], v[140:141] op_sel:[0,1] op_sel_hi:[1,0]
	v_mov_b64_e32 v[140:141], v[176:177]
	v_mov_b64_e32 v[142:143], v[178:179]
	v_mov_b32_e32 v144, v141
	v_mov_b32_e32 v145, v142
	v_mov_b32_e32 v141, v143
	v_pk_add_f32 v[140:141], v[144:145], v[140:141]
	v_mov_b64_e32 v[144:145], v[180:181]
	v_mov_b64_e32 v[146:147], v[182:183]
	v_pk_add_f32 v[142:143], v[140:141], v[140:141] op_sel:[0,1] op_sel_hi:[1,0]
	v_mov_b32_e32 v140, v145
	v_mov_b32_e32 v141, v146
	v_mov_b32_e32 v145, v147
	v_pk_add_f32 v[140:141], v[140:141], v[144:145]
	s_nop 0
	v_pk_add_f32 v[146:147], v[140:141], v[140:141] op_sel:[0,1] op_sel_hi:[1,0]
	v_mov_b32_e32 v140, v157
	v_mov_b32_e32 v141, v158
	v_mov_b32_e32 v157, v159
	v_pk_add_f32 v[140:141], v[140:141], v[156:157]
	v_mov_b64_e32 v[156:157], v[184:185]
	v_mov_b64_e32 v[158:159], v[186:187]
	v_pk_add_f32 v[140:141], v[140:141], v[140:141] op_sel:[0,1] op_sel_hi:[1,0]
	v_mov_b32_e32 v144, v157
	v_mov_b32_e32 v141, v150
	s_nop 1
	v_permlane16_swap_b32_e32 v150, v141
	v_add_f32_e32 v151, v150, v141
	v_mov_b32_e32 v141, v160
	s_nop 1
	v_permlane16_swap_b32_e32 v160, v141
	v_mov_b32_e32 v145, v158
	v_mov_b32_e32 v157, v159
	v_add_f32_e32 v150, v160, v141
	v_pk_add_f32 v[144:145], v[144:145], v[156:157]
	v_mov_b32_e32 v157, v151
	v_mov_b32_e32 v156, v150
	s_nop 0
	v_permlane32_swap_b32_e32 v151, v157
	v_permlane32_swap_b32_e32 v150, v156
	v_pk_add_f32 v[156:157], v[150:151], v[156:157]
	v_mov_b64_e32 v[150:151], s[0:1]
	v_pk_fma_f32 v[156:157], v[156:157], s[18:19], v[150:151] op_sel_hi:[1,0,0]
	v_pk_add_f32 v[144:145], v[144:145], v[144:145] op_sel:[0,1] op_sel_hi:[1,0]
	v_mul_f32_e32 v141, 0x4b800000, v157
	v_cmp_gt_f32_e64 s[0:1], s33, v157
	v_cmp_gt_f32_e32 vcc, s33, v156
	s_nop 0
	v_cndmask_b32_e64 v141, v157, v141, s[0:1]
	v_rsq_f32_e32 v141, v141
	s_nop 0
	v_mul_f32_e32 v143, 0x45800000, v141
	v_cndmask_b32_e64 v149, v141, v143, s[0:1]
	v_mul_f32_e32 v141, 0x4b800000, v156
	v_cndmask_b32_e32 v141, v156, v141, vcc
	v_rsq_f32_e32 v141, v141
	s_nop 0
	v_mul_f32_e32 v143, 0x45800000, v141
	v_cndmask_b32_e32 v147, v141, v143, vcc
	v_mov_b32_e32 v141, v152
	s_nop 1
	v_permlane16_swap_b32_e32 v152, v141
	v_add_f32_e32 v153, v152, v141
	v_mov_b32_e32 v141, v148
	s_nop 1
	v_permlane16_swap_b32_e32 v148, v141
	v_add_f32_e32 v152, v148, v141
	v_mov_b32_e32 v157, v153
	v_mov_b32_e32 v156, v152
	s_nop 0
	v_permlane32_swap_b32_e32 v153, v157
	v_permlane32_swap_b32_e32 v152, v156
	v_pk_add_f32 v[152:153], v[152:153], v[156:157]
	s_nop 0
	v_pk_fma_f32 v[152:153], v[152:153], s[18:19], v[150:151] op_sel_hi:[1,0,0]
	s_nop 0
	v_mul_f32_e32 v141, 0x4b800000, v153
	v_cmp_gt_f32_e64 s[0:1], s33, v153
	v_cmp_gt_f32_e32 vcc, s33, v152
	s_nop 0
	v_cndmask_b32_e64 v141, v153, v141, s[0:1]
	v_rsq_f32_e32 v141, v141
	s_nop 0
	v_mul_f32_e32 v143, 0x45800000, v141
	v_cndmask_b32_e64 v148, v141, v143, s[0:1]
	v_mul_f32_e32 v141, 0x4b800000, v152
	v_cndmask_b32_e32 v141, v152, v141, vcc
	v_rsq_f32_e32 v141, v141
	s_nop 0
	v_mul_f32_e32 v143, 0x45800000, v141
	v_cndmask_b32_e32 v145, v141, v143, vcc
	v_mov_b32_e32 v141, v142
	s_nop 1
	v_permlane16_swap_b32_e32 v142, v141
	v_add_f32_e32 v143, v142, v141
	v_mov_b32_e32 v141, v146
	s_nop 1
	v_permlane16_swap_b32_e32 v146, v141
	v_add_f32_e32 v142, v146, v141
	v_mov_b32_e32 v153, v143
	v_mov_b32_e32 v152, v142
	s_nop 0
	v_permlane32_swap_b32_e32 v143, v153
	v_permlane32_swap_b32_e32 v142, v152
	v_pk_add_f32 v[142:143], v[142:143], v[152:153]
	s_nop 0
	v_pk_fma_f32 v[142:143], v[142:143], s[18:19], v[150:151] op_sel_hi:[1,0,0]
	s_nop 0
	v_mul_f32_e32 v141, 0x4b800000, v143
	v_cmp_gt_f32_e64 s[0:1], s33, v143
	v_cmp_gt_f32_e32 vcc, s33, v142
	s_nop 0
	v_cndmask_b32_e64 v141, v143, v141, s[0:1]
; __device__ __forceinline__ unsigned pk2(float lo, float hi) { f32x2 v = {lo, hi}; bf16x2_t b = __builtin_convertvector(v, bf16x2_t); return __builtin_bit_cast(unsigned, b); }
; #define SG_(t) __builtin_amdgcn_rcpf(1.f + __builtin_amdgcn_exp2f(min2f(t, 19.931568f)))
; template <int NP> __device__ __forceinline__ void row_scales(float (&rs)[2][4], const float* base, long row0, int fq, float inv_n) {
;     float t[2][4];
; #pragma unroll
;     for (int ai = 0; ai < 2; ++ai)
; #pragma unroll
;         for (int m = 0; m < 4; ++m) { const long row = row0 + ai * 128 + m * 16;
;             if (NP == 16) { const f32x4 v = *(const f32x4*)(base + row * 16 + 4 * fq); t[ai][m] = (v.x + v.y) + (v.z + v.w); }
;             else if (NP == 8) { const f32x2 v = *(const f32x2*)(base + row * 8 + 2 * fq); t[ai][m] = v.x + v.y; }
;             else t[ai][m] = base[row * 4 + fq]; }
; #pragma unroll
;     for (int ai = 0; ai < 2; ++ai)
; #pragma unroll
;         for (int m = 0; m < 4; ++m) rs[ai][m] = rsqrtf(red_fq(t[ai][m]) * inv_n + EPS);
;     __device__ __forceinline__ void operator()(AccT& acc, const Unit& u, int wr, int wc, int fr, int fq, LAS unsigned char*) const {
;     ...
;             for (int m = 0; m < 4; ++m) {
;                 const float rs = rsa[ai][m] * -LOG2E;
;     ...
; #pragma unroll
;                 for (int bj = 0; bj < 2; ++bj) { const f32x4 v0 = acc[ai][bj][m][0] * rs, v1 = acc[ai][bj][m][1] * rs; u32x4 w;
;                     w.x = pk2(SG_(v0.x), SG_(v0.y)); w.y = pk2(SG_(v0.z), SG_(v0.w)); w.z = pk2(SG_(v1.x), SG_(v1.y)); w.w = pk2(SG_(v1.z), SG_(v1.w));
;     ...
;                     *(u32x4*)(gates + ((tb + (ai * 4 + m) * 2 + bj) * 64 + lane) * 8) = w; }
	v_rsq_f32_e32 v141, v141
	s_nop 0
	v_mul_f32_e32 v143, 0x45800000, v141
	v_cndmask_b32_e64 v143, v141, v143, s[0:1]
	v_mul_f32_e32 v141, 0x4b800000, v142
	v_cndmask_b32_e32 v141, v142, v141, vcc
	v_rsq_f32_e32 v141, v141
	s_nop 0
	v_mul_f32_e32 v142, 0x45800000, v141
	v_cndmask_b32_e32 v142, v141, v142, vcc
	v_mov_b32_e32 v141, v140
	s_nop 1
	v_permlane16_swap_b32_e32 v140, v141
	v_add_f32_e32 v141, v140, v141
	v_mov_b32_e32 v140, v144
	s_nop 1
	v_permlane16_swap_b32_e32 v144, v140
	v_add_f32_e32 v140, v144, v140
	v_mov_b32_e32 v153, v141
	v_mov_b32_e32 v152, v140
	s_nop 0
	v_permlane32_swap_b32_e32 v141, v153
	v_permlane32_swap_b32_e32 v140, v152
	v_pk_add_f32 v[140:141], v[140:141], v[152:153]
	s_nop 0
	v_pk_fma_f32 v[140:141], v[140:141], s[18:19], v[150:151] op_sel_hi:[1,0,0]
	s_nop 0
	v_mul_f32_e32 v144, 0x4b800000, v141
	v_cmp_gt_f32_e64 s[0:1], s33, v141
	v_cmp_gt_f32_e32 vcc, s33, v140
	s_nop 0
	v_cndmask_b32_e64 v141, v141, v144, s[0:1]
	v_rsq_f32_e32 v141, v141
	s_nop 0
	v_mul_f32_e32 v144, 0x45800000, v141
	v_cndmask_b32_e64 v141, v141, v144, s[0:1]
	v_mul_f32_e32 v144, 0x4b800000, v140
	v_cndmask_b32_e32 v140, v140, v144, vcc
	v_rsq_f32_e32 v140, v140
	s_add_u32 s0, s2, s12
	s_addc_u32 s1, s55, s13
	v_mul_f32_e32 v144, 0x45800000, v140
	v_cndmask_b32_e32 v140, v140, v144, vcc
	v_mul_f32_e32 v144, 0xbfb8aa3b, v149
	v_pk_mul_f32 v[126:127], v[126:127], v[144:145] op_sel_hi:[1,0]
	v_pk_mul_f32 v[150:151], v[124:125], v[144:145] op_sel_hi:[1,0]
	v_min_f32_e32 v124, v126, v246
	v_min_f32_e32 v125, v127, v246
	v_pk_mul_f32 v[122:123], v[122:123], v[144:145] op_sel_hi:[1,0]
	v_exp_f32_e32 v124, v124
	v_exp_f32_e32 v125, v125
	v_pk_mul_f32 v[128:129], v[128:129], v[144:145] op_sel_hi:[1,0]
	v_min_f32_e32 v122, v122, v246
	v_add_f32_e32 v124, 1.0, v124
	v_add_f32_e32 v125, 1.0, v125
	v_rcp_f32_e32 v124, v124
	v_rcp_f32_e32 v125, v125
	v_min_f32_e32 v126, v129, v246
	v_min_f32_e32 v123, v123, v246
	v_exp_f32_e32 v122, v122
	v_cvt_pk_bf16_f32 v124, v124, v125
	v_min_f32_e32 v125, v128, v246
	v_exp_f32_e32 v126, v126
	v_exp_f32_e32 v125, v125
	v_exp_f32_e32 v123, v123
	v_add_f32_e32 v122, 1.0, v122
	v_add_f32_e32 v126, 1.0, v126
	v_add_f32_e32 v125, 1.0, v125
	v_add_f32_e32 v123, 1.0, v123
	v_rcp_f32_e32 v125, v125
	v_rcp_f32_e32 v126, v126
	v_rcp_f32_e32 v122, v122
	v_rcp_f32_e32 v123, v123
	v_pk_mul_f32 v[118:119], v[118:119], v[144:145] op_sel_hi:[1,0]
	v_cvt_pk_bf16_f32 v125, v125, v126
	v_pk_mul_f32 v[120:121], v[120:121], v[144:145] op_sel_hi:[1,0]
	v_cvt_pk_bf16_f32 v126, v122, v123
	v_min_f32_e32 v122, v150, v246
	v_min_f32_e32 v123, v151, v246
	v_exp_f32_e32 v122, v122
	v_exp_f32_e32 v123, v123
	v_add_f32_e32 v122, 1.0, v122
	v_add_f32_e32 v123, 1.0, v123
	v_rcp_f32_e32 v122, v122
	v_rcp_f32_e32 v123, v123
	s_nop 0
	v_cvt_pk_bf16_f32 v127, v122, v123
	global_store_dwordx4 v0, v[124:127], s[0:1]
	v_lshl_add_u64 v[122:123], s[0:1], 0, v[0:1]
	s_nop 0
	v_pk_mul_f32 v[124:125], v[116:117], v[144:145] op_sel_hi:[1,0]
	v_pk_mul_f32 v[116:117], v[114:115], v[144:145] op_sel_hi:[1,0]
	v_min_f32_e32 v114, v118, v246
	v_min_f32_e32 v115, v119, v246
	v_min_f32_e32 v118, v121, v246
	v_exp_f32_e32 v114, v114
	v_exp_f32_e32 v115, v115
	v_min_f32_e32 v116, v116, v246
	v_min_f32_e32 v117, v117, v246
	v_add_f32_e32 v114, 1.0, v114
	v_add_f32_e32 v115, 1.0, v115
	v_rcp_f32_e32 v114, v114
	v_rcp_f32_e32 v115, v115
	v_exp_f32_e32 v118, v118
	v_exp_f32_e32 v116, v116
	v_exp_f32_e32 v117, v117
	v_cvt_pk_bf16_f32 v114, v114, v115
	v_min_f32_e32 v115, v120, v246
	v_add_f32_e32 v118, 1.0, v118
	v_exp_f32_e32 v115, v115
	v_add_f32_e32 v116, 1.0, v116
	v_add_f32_e32 v117, 1.0, v117
	v_rcp_f32_e32 v118, v118
	v_add_f32_e32 v115, 1.0, v115
	v_rcp_f32_e32 v115, v115
	v_rcp_f32_e32 v116, v116
	v_rcp_f32_e32 v117, v117
	v_cvt_pk_bf16_f32 v115, v115, v118
	v_min_f32_e32 v118, v125, v246
	v_cvt_pk_bf16_f32 v116, v116, v117
	v_min_f32_e32 v117, v124, v246
	v_exp_f32_e32 v118, v118
	v_exp_f32_e32 v117, v117
	v_add_f32_e32 v118, 1.0, v118
	v_add_f32_e32 v117, 1.0, v117
	v_rcp_f32_e32 v117, v117
	v_rcp_f32_e32 v118, v118
	s_nop 0
	v_cvt_pk_bf16_f32 v117, v117, v118
	global_store_dwordx4 v0, v[114:117], s[0:1] offset:1024
	s_nop 1
	v_mul_f32_e32 v114, 0xbfb8aa3b, v147
	v_pk_mul_f32 v[110:111], v[110:111], v[114:115] op_sel_hi:[1,0]
	v_pk_mul_f32 v[116:117], v[108:109], v[114:115] op_sel_hi:[1,0]
	v_pk_mul_f32 v[108:109], v[106:107], v[114:115] op_sel_hi:[1,0]
	v_min_f32_e32 v106, v110, v246
	v_min_f32_e32 v107, v111, v246
	v_pk_mul_f32 v[112:113], v[112:113], v[114:115] op_sel_hi:[1,0]
	v_exp_f32_e32 v106, v106
	v_exp_f32_e32 v107, v107
	v_min_f32_e32 v110, v113, v246
	v_min_f32_e32 v108, v108, v246
	v_add_f32_e32 v106, 1.0, v106
	v_add_f32_e32 v107, 1.0, v107
	v_rcp_f32_e32 v106, v106
	v_rcp_f32_e32 v107, v107
	v_min_f32_e32 v109, v109, v246
	v_exp_f32_e32 v110, v110
	v_exp_f32_e32 v108, v108
	v_cvt_pk_bf16_f32 v106, v106, v107
	v_min_f32_e32 v107, v112, v246
	v_exp_f32_e32 v109, v109
	v_exp_f32_e32 v107, v107
	v_add_f32_e32 v110, 1.0, v110
	v_add_f32_e32 v108, 1.0, v108
	v_add_f32_e32 v109, 1.0, v109
	v_add_f32_e32 v107, 1.0, v107
	v_rcp_f32_e32 v107, v107
	v_rcp_f32_e32 v110, v110
	v_rcp_f32_e32 v108, v108
	v_rcp_f32_e32 v109, v109
	v_pk_mul_f32 v[102:103], v[102:103], v[114:115] op_sel_hi:[1,0]
	v_cvt_pk_bf16_f32 v107, v107, v110
	v_min_f32_e32 v110, v117, v246
	v_cvt_pk_bf16_f32 v108, v108, v109
	v_min_f32_e32 v109, v116, v246
	v_exp_f32_e32 v110, v110
	v_exp_f32_e32 v109, v109
	v_pk_mul_f32 v[104:105], v[104:105], v[114:115] op_sel_hi:[1,0]
	v_add_f32_e32 v110, 1.0, v110
	v_add_f32_e32 v109, 1.0, v109
	v_rcp_f32_e32 v109, v109
	v_rcp_f32_e32 v110, v110
; __device__ __forceinline__ unsigned pk2(float lo, float hi) { f32x2 v = {lo, hi}; bf16x2_t b = __builtin_convertvector(v, bf16x2_t); return __builtin_bit_cast(unsigned, b); }
; #define SG_(t) __builtin_amdgcn_rcpf(1.f + __builtin_amdgcn_exp2f(min2f(t, 19.931568f)))
;     __device__ __forceinline__ void operator()(AccT& acc, const Unit& u, int wr, int wc, int fr, int fq, LAS unsigned char*) const {
;     ...
;             for (int m = 0; m < 4; ++m) {
;                 const float rs = rsa[ai][m] * -LOG2E;
;     ...
; #pragma unroll
;                 for (int bj = 0; bj < 2; ++bj) { const f32x4 v0 = acc[ai][bj][m][0] * rs, v1 = acc[ai][bj][m][1] * rs; u32x4 w;
;                     w.x = pk2(SG_(v0.x), SG_(v0.y)); w.y = pk2(SG_(v0.z), SG_(v0.w)); w.z = pk2(SG_(v1.x), SG_(v1.y)); w.w = pk2(SG_(v1.z), SG_(v1.w));
;     ...
;                     *(u32x4*)(gates + ((tb + (ai * 4 + m) * 2 + bj) * 64 + lane) * 8) = w; }
	s_nop 0
	v_cvt_pk_bf16_f32 v109, v109, v110
	global_store_dwordx4 v0, v[106:109], s[0:1] offset:2048
	s_nop 1
	v_pk_mul_f32 v[106:107], v[100:101], v[114:115] op_sel_hi:[1,0]
	v_pk_mul_f32 v[100:101], v[98:99], v[114:115] op_sel_hi:[1,0]
	v_min_f32_e32 v98, v102, v246
	v_min_f32_e32 v99, v103, v246
	v_min_f32_e32 v102, v105, v246
	v_exp_f32_e32 v98, v98
	v_exp_f32_e32 v99, v99
	v_min_f32_e32 v100, v100, v246
	v_min_f32_e32 v101, v101, v246
	v_add_f32_e32 v98, 1.0, v98
	v_add_f32_e32 v99, 1.0, v99
	v_rcp_f32_e32 v98, v98
	v_rcp_f32_e32 v99, v99
	v_exp_f32_e32 v102, v102
	v_exp_f32_e32 v100, v100
	v_exp_f32_e32 v101, v101
	v_cvt_pk_bf16_f32 v98, v98, v99
	v_min_f32_e32 v99, v104, v246
	v_add_f32_e32 v102, 1.0, v102
	v_exp_f32_e32 v99, v99
	v_add_f32_e32 v100, 1.0, v100
	v_add_f32_e32 v101, 1.0, v101
	v_rcp_f32_e32 v102, v102
	v_add_f32_e32 v99, 1.0, v99
	v_rcp_f32_e32 v99, v99
	v_rcp_f32_e32 v100, v100
	v_rcp_f32_e32 v101, v101
	v_cvt_pk_bf16_f32 v99, v99, v102
	v_min_f32_e32 v102, v107, v246
	v_cvt_pk_bf16_f32 v100, v100, v101
	v_min_f32_e32 v101, v106, v246
	v_exp_f32_e32 v102, v102
	v_exp_f32_e32 v101, v101
	v_add_f32_e32 v102, 1.0, v102
	v_add_f32_e32 v101, 1.0, v101
	v_rcp_f32_e32 v101, v101
	v_rcp_f32_e32 v102, v102
	s_nop 0
	v_cvt_pk_bf16_f32 v101, v101, v102
	global_store_dwordx4 v0, v[98:101], s[0:1] offset:3072
	s_movk_i32 s0, 0x1000
	s_nop 0
	v_mul_f32_e32 v98, 0xbfb8aa3b, v148
	v_pk_mul_f32 v[94:95], v[94:95], v[98:99] op_sel_hi:[1,0]
	v_pk_mul_f32 v[96:97], v[96:97], v[98:99] op_sel_hi:[1,0]
	v_min_f32_e32 v94, v94, v246
	v_min_f32_e32 v95, v95, v246
	v_pk_mul_f32 v[90:91], v[90:91], v[98:99] op_sel_hi:[1,0]
	v_exp_f32_e32 v94, v94
	v_exp_f32_e32 v95, v95
	v_min_f32_e32 v90, v90, v246
	v_min_f32_e32 v91, v91, v246
	v_add_f32_e32 v94, 1.0, v94
	v_add_f32_e32 v95, 1.0, v95
	v_rcp_f32_e32 v94, v94
	v_rcp_f32_e32 v95, v95
	v_exp_f32_e32 v90, v90
	v_exp_f32_e32 v91, v91
	v_pk_mul_f32 v[92:93], v[92:93], v[98:99] op_sel_hi:[1,0]
	v_cvt_pk_bf16_f32 v94, v94, v95
	v_min_f32_e32 v95, v96, v246
	v_min_f32_e32 v96, v97, v246
	v_add_f32_e32 v90, 1.0, v90
	v_exp_f32_e32 v95, v95
	v_exp_f32_e32 v96, v96
	v_add_f32_e32 v91, 1.0, v91
	v_rcp_f32_e32 v90, v90
	v_add_f32_e32 v95, 1.0, v95
	v_add_f32_e32 v96, 1.0, v96
	v_rcp_f32_e32 v95, v95
	v_rcp_f32_e32 v96, v96
	v_rcp_f32_e32 v91, v91
	v_pk_mul_f32 v[86:87], v[86:87], v[98:99] op_sel_hi:[1,0]
	v_pk_mul_f32 v[88:89], v[88:89], v[98:99] op_sel_hi:[1,0]
	v_cvt_pk_bf16_f32 v95, v95, v96
	v_cvt_pk_bf16_f32 v96, v90, v91
	v_min_f32_e32 v90, v92, v246
	v_min_f32_e32 v91, v93, v246
	v_add_co_u32_e32 v92, vcc, s0, v122
	v_exp_f32_e32 v90, v90
	v_exp_f32_e32 v91, v91
	v_addc_co_u32_e32 v93, vcc, 0, v123, vcc
	v_add_f32_e32 v90, 1.0, v90
	v_add_f32_e32 v91, 1.0, v91
	v_rcp_f32_e32 v90, v90
	v_rcp_f32_e32 v91, v91
	s_movk_i32 s0, 0x3000
	v_cvt_pk_bf16_f32 v97, v90, v91
	v_add_co_u32_e32 v90, vcc, s8, v122
	s_nop 1
	v_addc_co_u32_e32 v91, vcc, 0, v123, vcc
	global_store_dwordx4 v[90:91], v[94:97], off offset:-4096
	s_nop 1
	v_pk_mul_f32 v[94:95], v[84:85], v[98:99] op_sel_hi:[1,0]
	v_pk_mul_f32 v[84:85], v[82:83], v[98:99] op_sel_hi:[1,0]
	v_min_f32_e32 v82, v86, v246
	v_min_f32_e32 v83, v87, v246
	v_min_f32_e32 v86, v89, v246
	v_exp_f32_e32 v82, v82
	v_exp_f32_e32 v83, v83
	v_min_f32_e32 v84, v84, v246
	v_min_f32_e32 v85, v85, v246
	v_add_f32_e32 v82, 1.0, v82
	v_add_f32_e32 v83, 1.0, v83
	v_rcp_f32_e32 v82, v82
	v_rcp_f32_e32 v83, v83
	v_exp_f32_e32 v86, v86
	v_exp_f32_e32 v84, v84
	v_exp_f32_e32 v85, v85
	v_cvt_pk_bf16_f32 v82, v82, v83
	v_min_f32_e32 v83, v88, v246
	v_add_f32_e32 v86, 1.0, v86
	v_exp_f32_e32 v83, v83
	v_add_f32_e32 v84, 1.0, v84
	v_add_f32_e32 v85, 1.0, v85
	v_rcp_f32_e32 v86, v86
	v_add_f32_e32 v83, 1.0, v83
	v_rcp_f32_e32 v83, v83
	v_rcp_f32_e32 v84, v84
	v_rcp_f32_e32 v85, v85
	v_cvt_pk_bf16_f32 v83, v83, v86
	v_min_f32_e32 v86, v95, v246
	v_cvt_pk_bf16_f32 v84, v84, v85
	v_min_f32_e32 v85, v94, v246
	v_exp_f32_e32 v86, v86
	v_exp_f32_e32 v85, v85
	v_add_f32_e32 v86, 1.0, v86
	v_add_f32_e32 v85, 1.0, v85
	v_rcp_f32_e32 v85, v85
	v_rcp_f32_e32 v86, v86
	s_nop 0
	v_cvt_pk_bf16_f32 v85, v85, v86
	global_store_dwordx4 v[92:93], v[82:85], off offset:1024
	s_nop 1
	v_mul_f32_e32 v82, 0xbfb8aa3b, v145
	v_pk_mul_f32 v[78:79], v[78:79], v[82:83] op_sel_hi:[1,0]
	v_pk_mul_f32 v[84:85], v[76:77], v[82:83] op_sel_hi:[1,0]
	v_pk_mul_f32 v[76:77], v[74:75], v[82:83] op_sel_hi:[1,0]
	v_min_f32_e32 v74, v78, v246
	v_min_f32_e32 v75, v79, v246
	v_pk_mul_f32 v[80:81], v[80:81], v[82:83] op_sel_hi:[1,0]
	v_exp_f32_e32 v74, v74
	v_exp_f32_e32 v75, v75
	v_min_f32_e32 v78, v81, v246
	v_min_f32_e32 v76, v76, v246
	v_add_f32_e32 v74, 1.0, v74
	v_add_f32_e32 v75, 1.0, v75
	v_rcp_f32_e32 v74, v74
	v_rcp_f32_e32 v75, v75
	v_min_f32_e32 v77, v77, v246
	v_exp_f32_e32 v78, v78
	v_exp_f32_e32 v76, v76
	v_cvt_pk_bf16_f32 v74, v74, v75
	v_min_f32_e32 v75, v80, v246
	v_exp_f32_e32 v77, v77
	v_exp_f32_e32 v75, v75
	v_add_f32_e32 v78, 1.0, v78
	v_add_f32_e32 v76, 1.0, v76
	v_add_f32_e32 v77, 1.0, v77
	v_add_f32_e32 v75, 1.0, v75
	v_rcp_f32_e32 v75, v75
	v_rcp_f32_e32 v78, v78
	v_rcp_f32_e32 v76, v76
	v_rcp_f32_e32 v77, v77
	v_pk_mul_f32 v[70:71], v[70:71], v[82:83] op_sel_hi:[1,0]
	v_cvt_pk_bf16_f32 v75, v75, v78
	v_min_f32_e32 v78, v85, v246
	v_cvt_pk_bf16_f32 v76, v76, v77
	v_min_f32_e32 v77, v84, v246
	v_exp_f32_e32 v78, v78
	v_exp_f32_e32 v77, v77
	v_pk_mul_f32 v[72:73], v[72:73], v[82:83] op_sel_hi:[1,0]
	v_add_f32_e32 v78, 1.0, v78
	v_add_f32_e32 v77, 1.0, v77
	v_rcp_f32_e32 v77, v77
	v_rcp_f32_e32 v78, v78
	s_nop 0
	v_cvt_pk_bf16_f32 v77, v77, v78
	global_store_dwordx4 v[92:93], v[74:77], off offset:2048
; __device__ __forceinline__ unsigned pk2(float lo, float hi) { f32x2 v = {lo, hi}; bf16x2_t b = __builtin_convertvector(v, bf16x2_t); return __builtin_bit_cast(unsigned, b); }
; #define SG_(t) __builtin_amdgcn_rcpf(1.f + __builtin_amdgcn_exp2f(min2f(t, 19.931568f)))
;     __device__ __forceinline__ void operator()(AccT& acc, const Unit& u, int wr, int wc, int fr, int fq, LAS unsigned char*) const {
;     ...
;             for (int m = 0; m < 4; ++m) {
;                 const float rs = rsa[ai][m] * -LOG2E;
;     ...
; #pragma unroll
;                 for (int bj = 0; bj < 2; ++bj) { const f32x4 v0 = acc[ai][bj][m][0] * rs, v1 = acc[ai][bj][m][1] * rs; u32x4 w;
;                     w.x = pk2(SG_(v0.x), SG_(v0.y)); w.y = pk2(SG_(v0.z), SG_(v0.w)); w.z = pk2(SG_(v1.x), SG_(v1.y)); w.w = pk2(SG_(v1.z), SG_(v1.w));
;     ...
;                     *(u32x4*)(gates + ((tb + (ai * 4 + m) * 2 + bj) * 64 + lane) * 8) = w; }
	s_nop 1
	v_pk_mul_f32 v[74:75], v[68:69], v[82:83] op_sel_hi:[1,0]
	v_pk_mul_f32 v[68:69], v[66:67], v[82:83] op_sel_hi:[1,0]
	v_min_f32_e32 v66, v70, v246
	v_min_f32_e32 v67, v71, v246
	v_min_f32_e32 v70, v73, v246
	v_exp_f32_e32 v66, v66
	v_exp_f32_e32 v67, v67
	v_min_f32_e32 v68, v68, v246
	v_min_f32_e32 v69, v69, v246
	v_add_f32_e32 v66, 1.0, v66
	v_add_f32_e32 v67, 1.0, v67
	v_rcp_f32_e32 v66, v66
	v_rcp_f32_e32 v67, v67
	v_exp_f32_e32 v70, v70
	v_exp_f32_e32 v68, v68
	v_exp_f32_e32 v69, v69
	v_cvt_pk_bf16_f32 v66, v66, v67
	v_min_f32_e32 v67, v72, v246
	v_add_f32_e32 v70, 1.0, v70
	v_exp_f32_e32 v67, v67
	v_add_f32_e32 v68, 1.0, v68
	v_add_f32_e32 v69, 1.0, v69
	v_rcp_f32_e32 v70, v70
	v_add_f32_e32 v67, 1.0, v67
	v_rcp_f32_e32 v67, v67
	v_rcp_f32_e32 v68, v68
	v_rcp_f32_e32 v69, v69
	v_cvt_pk_bf16_f32 v67, v67, v70
	v_min_f32_e32 v70, v75, v246
	v_cvt_pk_bf16_f32 v68, v68, v69
	v_min_f32_e32 v69, v74, v246
	v_exp_f32_e32 v70, v70
	v_exp_f32_e32 v69, v69
	v_add_f32_e32 v70, 1.0, v70
	v_add_f32_e32 v69, 1.0, v69
	v_rcp_f32_e32 v69, v69
	v_rcp_f32_e32 v70, v70
	s_nop 0
	v_cvt_pk_bf16_f32 v69, v69, v70
	global_store_dwordx4 v[92:93], v[66:69], off offset:3072
	s_nop 1
	v_mul_f32_e32 v66, 0xbfb8aa3b, v143
	v_pk_mul_f32 v[62:63], v[62:63], v[66:67] op_sel_hi:[1,0]
	v_pk_mul_f32 v[68:69], v[60:61], v[66:67] op_sel_hi:[1,0]
	v_pk_mul_f32 v[60:61], v[58:59], v[66:67] op_sel_hi:[1,0]
	v_min_f32_e32 v58, v62, v246
	v_min_f32_e32 v59, v63, v246
	v_pk_mul_f32 v[64:65], v[64:65], v[66:67] op_sel_hi:[1,0]
	v_exp_f32_e32 v58, v58
	v_exp_f32_e32 v59, v59
	v_min_f32_e32 v62, v65, v246
	v_min_f32_e32 v60, v60, v246
	v_add_f32_e32 v58, 1.0, v58
	v_add_f32_e32 v59, 1.0, v59
	v_rcp_f32_e32 v58, v58
	v_rcp_f32_e32 v59, v59
	v_min_f32_e32 v61, v61, v246
	v_exp_f32_e32 v62, v62
	v_exp_f32_e32 v60, v60
	v_cvt_pk_bf16_f32 v58, v58, v59
	v_min_f32_e32 v59, v64, v246
	v_exp_f32_e32 v61, v61
	v_exp_f32_e32 v59, v59
	v_add_f32_e32 v62, 1.0, v62
	v_add_f32_e32 v60, 1.0, v60
	v_add_f32_e32 v61, 1.0, v61
	v_add_f32_e32 v59, 1.0, v59
	v_rcp_f32_e32 v59, v59
	v_rcp_f32_e32 v62, v62
	v_rcp_f32_e32 v60, v60
	v_rcp_f32_e32 v61, v61
	v_pk_mul_f32 v[54:55], v[54:55], v[66:67] op_sel_hi:[1,0]
	v_cvt_pk_bf16_f32 v59, v59, v62
	v_min_f32_e32 v62, v69, v246
	v_cvt_pk_bf16_f32 v60, v60, v61
	v_min_f32_e32 v61, v68, v246
	v_exp_f32_e32 v62, v62
	v_exp_f32_e32 v61, v61
	v_pk_mul_f32 v[56:57], v[56:57], v[66:67] op_sel_hi:[1,0]
	v_add_f32_e32 v62, 1.0, v62
	v_add_f32_e32 v61, 1.0, v61
	v_rcp_f32_e32 v61, v61
	v_rcp_f32_e32 v62, v62
	s_nop 0
	v_cvt_pk_bf16_f32 v61, v61, v62
	global_store_dwordx4 v[90:91], v[58:61], off
	s_nop 1
	v_pk_mul_f32 v[58:59], v[52:53], v[66:67] op_sel_hi:[1,0]
	v_pk_mul_f32 v[52:53], v[50:51], v[66:67] op_sel_hi:[1,0]
	v_min_f32_e32 v50, v54, v246
	v_min_f32_e32 v51, v55, v246
	v_min_f32_e32 v54, v57, v246
	v_exp_f32_e32 v50, v50
	v_exp_f32_e32 v51, v51
	v_min_f32_e32 v52, v52, v246
	v_min_f32_e32 v53, v53, v246
	v_add_f32_e32 v50, 1.0, v50
	v_add_f32_e32 v51, 1.0, v51
	v_rcp_f32_e32 v50, v50
	v_rcp_f32_e32 v51, v51
	v_exp_f32_e32 v54, v54
	v_exp_f32_e32 v52, v52
	v_exp_f32_e32 v53, v53
	v_cvt_pk_bf16_f32 v50, v50, v51
	v_min_f32_e32 v51, v56, v246
	v_add_f32_e32 v54, 1.0, v54
	v_exp_f32_e32 v51, v51
	v_add_f32_e32 v52, 1.0, v52
	v_add_f32_e32 v53, 1.0, v53
	v_rcp_f32_e32 v54, v54
	v_add_f32_e32 v51, 1.0, v51
	v_rcp_f32_e32 v51, v51
	v_rcp_f32_e32 v52, v52
	v_rcp_f32_e32 v53, v53
	v_cvt_pk_bf16_f32 v51, v51, v54
	v_min_f32_e32 v54, v59, v246
	v_cvt_pk_bf16_f32 v52, v52, v53
	v_min_f32_e32 v53, v58, v246
	v_exp_f32_e32 v54, v54
	v_exp_f32_e32 v53, v53
	v_add_f32_e32 v54, 1.0, v54
	v_add_f32_e32 v53, 1.0, v53
	v_rcp_f32_e32 v53, v53
	v_rcp_f32_e32 v54, v54
	s_nop 0
	v_cvt_pk_bf16_f32 v53, v53, v54
	global_store_dwordx4 v[90:91], v[50:53], off offset:1024
	s_nop 1
	v_mul_f32_e32 v50, 0xbfb8aa3b, v142
	v_pk_mul_f32 v[46:47], v[46:47], v[50:51] op_sel_hi:[1,0]
	v_pk_mul_f32 v[52:53], v[44:45], v[50:51] op_sel_hi:[1,0]
	v_pk_mul_f32 v[44:45], v[42:43], v[50:51] op_sel_hi:[1,0]
	v_min_f32_e32 v42, v46, v246
	v_min_f32_e32 v43, v47, v246
	v_pk_mul_f32 v[48:49], v[48:49], v[50:51] op_sel_hi:[1,0]
	v_exp_f32_e32 v42, v42
	v_exp_f32_e32 v43, v43
	v_min_f32_e32 v46, v49, v246
	v_min_f32_e32 v44, v44, v246
	v_add_f32_e32 v42, 1.0, v42
	v_add_f32_e32 v43, 1.0, v43
	v_rcp_f32_e32 v42, v42
	v_rcp_f32_e32 v43, v43
	v_min_f32_e32 v45, v45, v246
	v_exp_f32_e32 v46, v46
	v_exp_f32_e32 v44, v44
	v_cvt_pk_bf16_f32 v42, v42, v43
	v_min_f32_e32 v43, v48, v246
	v_exp_f32_e32 v45, v45
	v_exp_f32_e32 v43, v43
	v_add_f32_e32 v46, 1.0, v46
	v_add_f32_e32 v44, 1.0, v44
	v_add_f32_e32 v45, 1.0, v45
	v_add_f32_e32 v43, 1.0, v43
	v_rcp_f32_e32 v43, v43
	v_rcp_f32_e32 v46, v46
	v_rcp_f32_e32 v44, v44
	v_rcp_f32_e32 v45, v45
	v_pk_mul_f32 v[38:39], v[38:39], v[50:51] op_sel_hi:[1,0]
	v_cvt_pk_bf16_f32 v43, v43, v46
	v_min_f32_e32 v46, v53, v246
	v_cvt_pk_bf16_f32 v44, v44, v45
	v_min_f32_e32 v45, v52, v246
	v_exp_f32_e32 v46, v46
	v_exp_f32_e32 v45, v45
	v_pk_mul_f32 v[40:41], v[40:41], v[50:51] op_sel_hi:[1,0]
	v_add_f32_e32 v46, 1.0, v46
	v_add_f32_e32 v45, 1.0, v45
	v_rcp_f32_e32 v45, v45
	v_rcp_f32_e32 v46, v46
	s_nop 0
	v_cvt_pk_bf16_f32 v45, v45, v46
	global_store_dwordx4 v[90:91], v[42:45], off offset:2048
	s_nop 1
	v_pk_mul_f32 v[42:43], v[36:37], v[50:51] op_sel_hi:[1,0]
	v_pk_mul_f32 v[36:37], v[34:35], v[50:51] op_sel_hi:[1,0]
	v_min_f32_e32 v34, v38, v246
	v_min_f32_e32 v35, v39, v246
	v_min_f32_e32 v38, v41, v246
	v_exp_f32_e32 v34, v34
	v_exp_f32_e32 v35, v35
	v_min_f32_e32 v36, v36, v246
	v_min_f32_e32 v37, v37, v246
	v_add_f32_e32 v34, 1.0, v34
	v_add_f32_e32 v35, 1.0, v35
; __device__ __forceinline__ unsigned pk2(float lo, float hi) { f32x2 v = {lo, hi}; bf16x2_t b = __builtin_convertvector(v, bf16x2_t); return __builtin_bit_cast(unsigned, b); }
; #define SG_(t) __builtin_amdgcn_rcpf(1.f + __builtin_amdgcn_exp2f(min2f(t, 19.931568f)))
;     __device__ __forceinline__ void operator()(AccT& acc, const Unit& u, int wr, int wc, int fr, int fq, LAS unsigned char*) const {
;     ...
;             for (int m = 0; m < 4; ++m) {
;                 const float rs = rsa[ai][m] * -LOG2E;
;     ...
; #pragma unroll
;                 for (int bj = 0; bj < 2; ++bj) { const f32x4 v0 = acc[ai][bj][m][0] * rs, v1 = acc[ai][bj][m][1] * rs; u32x4 w;
;                     w.x = pk2(SG_(v0.x), SG_(v0.y)); w.y = pk2(SG_(v0.z), SG_(v0.w)); w.z = pk2(SG_(v1.x), SG_(v1.y)); w.w = pk2(SG_(v1.z), SG_(v1.w));
;     ...
;                     *(u32x4*)(gates + ((tb + (ai * 4 + m) * 2 + bj) * 64 + lane) * 8) = w; }
;             }
	v_rcp_f32_e32 v34, v34
	v_rcp_f32_e32 v35, v35
	v_exp_f32_e32 v38, v38
	v_exp_f32_e32 v36, v36
	v_exp_f32_e32 v37, v37
	v_cvt_pk_bf16_f32 v34, v34, v35
	v_min_f32_e32 v35, v40, v246
	v_add_f32_e32 v38, 1.0, v38
	v_exp_f32_e32 v35, v35
	v_add_f32_e32 v36, 1.0, v36
	v_add_f32_e32 v37, 1.0, v37
	v_rcp_f32_e32 v38, v38
	v_add_f32_e32 v35, 1.0, v35
	v_rcp_f32_e32 v35, v35
	v_rcp_f32_e32 v36, v36
	v_rcp_f32_e32 v37, v37
	v_cvt_pk_bf16_f32 v35, v35, v38
	v_min_f32_e32 v38, v43, v246
	v_cvt_pk_bf16_f32 v36, v36, v37
	v_min_f32_e32 v37, v42, v246
	v_exp_f32_e32 v38, v38
	v_exp_f32_e32 v37, v37
	v_add_f32_e32 v38, 1.0, v38
	v_add_f32_e32 v37, 1.0, v37
	v_rcp_f32_e32 v37, v37
	v_rcp_f32_e32 v38, v38
	s_nop 0
	v_cvt_pk_bf16_f32 v37, v37, v38
	global_store_dwordx4 v[90:91], v[34:37], off offset:3072
	s_nop 1
	v_mul_f32_e32 v34, 0xbfb8aa3b, v141
	v_pk_mul_f32 v[30:31], v[30:31], v[34:35] op_sel_hi:[1,0]
	v_pk_mul_f32 v[36:37], v[28:29], v[34:35] op_sel_hi:[1,0]
	v_min_f32_e32 v28, v30, v246
	v_min_f32_e32 v29, v31, v246
	v_pk_mul_f32 v[26:27], v[26:27], v[34:35] op_sel_hi:[1,0]
	v_exp_f32_e32 v28, v28
	v_exp_f32_e32 v29, v29
	v_pk_mul_f32 v[32:33], v[32:33], v[34:35] op_sel_hi:[1,0]
	v_min_f32_e32 v26, v26, v246
	v_add_f32_e32 v28, 1.0, v28
	v_add_f32_e32 v29, 1.0, v29
	v_rcp_f32_e32 v28, v28
	v_rcp_f32_e32 v29, v29
	v_min_f32_e32 v30, v33, v246
	v_min_f32_e32 v27, v27, v246
	v_exp_f32_e32 v26, v26
	v_cvt_pk_bf16_f32 v28, v28, v29
	v_min_f32_e32 v29, v32, v246
	v_exp_f32_e32 v30, v30
	v_exp_f32_e32 v29, v29
	v_exp_f32_e32 v27, v27
	v_add_f32_e32 v26, 1.0, v26
	v_add_f32_e32 v30, 1.0, v30
	v_add_f32_e32 v29, 1.0, v29
	v_add_f32_e32 v27, 1.0, v27
	v_rcp_f32_e32 v29, v29
	v_rcp_f32_e32 v30, v30
	v_rcp_f32_e32 v26, v26
	v_rcp_f32_e32 v27, v27
	v_pk_mul_f32 v[22:23], v[22:23], v[34:35] op_sel_hi:[1,0]
	v_cvt_pk_bf16_f32 v29, v29, v30
	v_pk_mul_f32 v[24:25], v[24:25], v[34:35] op_sel_hi:[1,0]
	v_cvt_pk_bf16_f32 v30, v26, v27
	v_min_f32_e32 v26, v36, v246
	v_min_f32_e32 v27, v37, v246
	v_exp_f32_e32 v26, v26
	v_exp_f32_e32 v27, v27
	v_add_f32_e32 v26, 1.0, v26
	v_add_f32_e32 v27, 1.0, v27
	v_rcp_f32_e32 v26, v26
	v_rcp_f32_e32 v27, v27
	s_nop 0
	v_cvt_pk_bf16_f32 v31, v26, v27
	v_add_co_u32_e32 v26, vcc, s0, v122
	s_mov_b64 s[0:1], -1
	s_nop 0
	v_addc_co_u32_e32 v27, vcc, 0, v123, vcc
	global_store_dwordx4 v[26:27], v[28:31], off
	s_andn2_b64 vcc, exec, s[38:39]
	s_nop 0
	v_pk_mul_f32 v[28:29], v[20:21], v[34:35] op_sel_hi:[1,0]
	v_pk_mul_f32 v[20:21], v[18:19], v[34:35] op_sel_hi:[1,0]
	v_min_f32_e32 v18, v22, v246
	v_min_f32_e32 v19, v23, v246
	v_min_f32_e32 v22, v25, v246
	v_exp_f32_e32 v18, v18
	v_exp_f32_e32 v19, v19
	v_min_f32_e32 v20, v20, v246
	v_min_f32_e32 v21, v21, v246
	v_add_f32_e32 v18, 1.0, v18
	v_add_f32_e32 v19, 1.0, v19
	v_rcp_f32_e32 v18, v18
	v_rcp_f32_e32 v19, v19
	v_exp_f32_e32 v22, v22
	v_exp_f32_e32 v20, v20
	v_exp_f32_e32 v21, v21
	v_cvt_pk_bf16_f32 v18, v18, v19
	v_min_f32_e32 v19, v24, v246
	v_add_f32_e32 v22, 1.0, v22
	v_exp_f32_e32 v19, v19
	v_add_f32_e32 v20, 1.0, v20
	v_add_f32_e32 v21, 1.0, v21
	v_rcp_f32_e32 v22, v22
	v_add_f32_e32 v19, 1.0, v19
	v_rcp_f32_e32 v19, v19
	v_rcp_f32_e32 v20, v20
	v_rcp_f32_e32 v21, v21
	v_cvt_pk_bf16_f32 v19, v19, v22
	v_min_f32_e32 v22, v29, v246
	v_cvt_pk_bf16_f32 v20, v20, v21
	v_min_f32_e32 v21, v28, v246
	v_exp_f32_e32 v22, v22
	v_exp_f32_e32 v21, v21
	v_add_f32_e32 v22, 1.0, v22
	v_add_f32_e32 v21, 1.0, v21
	v_rcp_f32_e32 v21, v21
	v_rcp_f32_e32 v22, v22
	s_nop 0
	v_cvt_pk_bf16_f32 v21, v21, v22
	global_store_dwordx4 v[26:27], v[18:21], off offset:1024
	s_nop 1
	v_mul_f32_e32 v18, 0xbfb8aa3b, v140
	v_pk_mul_f32 v[14:15], v[14:15], v[18:19] op_sel_hi:[1,0]
	v_pk_mul_f32 v[20:21], v[12:13], v[18:19] op_sel_hi:[1,0]
	v_pk_mul_f32 v[12:13], v[10:11], v[18:19] op_sel_hi:[1,0]
	v_min_f32_e32 v10, v14, v246
	v_min_f32_e32 v11, v15, v246
	v_pk_mul_f32 v[16:17], v[16:17], v[18:19] op_sel_hi:[1,0]
	v_exp_f32_e32 v10, v10
	v_exp_f32_e32 v11, v11
	v_min_f32_e32 v14, v17, v246
	v_min_f32_e32 v12, v12, v246
	v_add_f32_e32 v10, 1.0, v10
	v_add_f32_e32 v11, 1.0, v11
	v_rcp_f32_e32 v10, v10
	v_rcp_f32_e32 v11, v11
	v_min_f32_e32 v13, v13, v246
	v_exp_f32_e32 v14, v14
	v_exp_f32_e32 v12, v12
	v_cvt_pk_bf16_f32 v10, v10, v11
	v_min_f32_e32 v11, v16, v246
	v_exp_f32_e32 v13, v13
	v_exp_f32_e32 v11, v11
	v_add_f32_e32 v14, 1.0, v14
	v_add_f32_e32 v12, 1.0, v12
	v_add_f32_e32 v13, 1.0, v13
	v_add_f32_e32 v11, 1.0, v11
	v_rcp_f32_e32 v11, v11
	v_rcp_f32_e32 v14, v14
	v_rcp_f32_e32 v12, v12
	v_rcp_f32_e32 v13, v13
	v_pk_mul_f32 v[6:7], v[6:7], v[18:19] op_sel_hi:[1,0]
	v_cvt_pk_bf16_f32 v11, v11, v14
	v_min_f32_e32 v14, v21, v246
	v_cvt_pk_bf16_f32 v12, v12, v13
	v_min_f32_e32 v13, v20, v246
	v_exp_f32_e32 v14, v14
	v_exp_f32_e32 v13, v13
	v_pk_mul_f32 v[8:9], v[8:9], v[18:19] op_sel_hi:[1,0]
	v_add_f32_e32 v14, 1.0, v14
	v_add_f32_e32 v13, 1.0, v13
	v_rcp_f32_e32 v13, v13
	v_rcp_f32_e32 v14, v14
	s_nop 0
	v_cvt_pk_bf16_f32 v13, v13, v14
	global_store_dwordx4 v[26:27], v[10:13], off offset:2048
	s_nop 1
	v_pk_mul_f32 v[10:11], v[4:5], v[18:19] op_sel_hi:[1,0]
	v_pk_mul_f32 v[4:5], v[2:3], v[18:19] op_sel_hi:[1,0]
	v_min_f32_e32 v2, v6, v246
	v_min_f32_e32 v3, v7, v246
	v_min_f32_e32 v6, v9, v246
	v_exp_f32_e32 v2, v2
	v_exp_f32_e32 v3, v3
	v_min_f32_e32 v4, v4, v246
	v_min_f32_e32 v5, v5, v246
	v_add_f32_e32 v2, 1.0, v2
	v_add_f32_e32 v3, 1.0, v3
	v_rcp_f32_e32 v2, v2
	v_rcp_f32_e32 v3, v3
	v_exp_f32_e32 v6, v6
	v_exp_f32_e32 v4, v4
	v_exp_f32_e32 v5, v5
	v_cvt_pk_bf16_f32 v2, v2, v3
	v_min_f32_e32 v3, v8, v246
	v_add_f32_e32 v6, 1.0, v6
	v_exp_f32_e32 v3, v3
	v_add_f32_e32 v4, 1.0, v4
	v_add_f32_e32 v5, 1.0, v5
	v_rcp_f32_e32 v6, v6
	v_add_f32_e32 v3, 1.0, v3
	v_rcp_f32_e32 v3, v3
	v_rcp_f32_e32 v4, v4
	v_rcp_f32_e32 v5, v5
	v_cvt_pk_bf16_f32 v3, v3, v6
	v_min_f32_e32 v6, v11, v246
	v_cvt_pk_bf16_f32 v4, v4, v5
	v_min_f32_e32 v5, v10, v246
	v_exp_f32_e32 v6, v6
	v_exp_f32_e32 v5, v5
	v_add_f32_e32 v6, 1.0, v6
	v_add_f32_e32 v5, 1.0, v5
	v_rcp_f32_e32 v5, v5
	v_rcp_f32_e32 v6, v6
	s_nop 0
	v_cvt_pk_bf16_f32 v5, v5, v6
	global_store_dwordx4 v[26:27], v[2:5], off offset:3072
	s_cbranch_vccnz .LBB0_328
	s_andn2_b64 vcc, exec, s[6:7]
	s_cbranch_vccnz .LBB0_327
	s_barrier
	s_branch .LBB0_327
